# speedup vs baseline: 1.0054x; 1.0054x over previous
; __device__ __forceinline__ void phase_gemms(int ph) {
;     ...
;   for (int it = blockIdx.x; it < total; it += gridDim.x) {
;     int l = tile_remap(it, total);
;     int which = 0, nM = nM0, nN = nN0, mode = mode0;
;     if (l >= n0) { which = 1; l -= n0; nM = nM1; nN = nN1; mode = mode1; }
;     int pm, pn;
;     tile_pmpn(l, nM, nN, pm, pn);
;     if (mode == 0) gemm_tile<0>(ph, which, pm, pn);
;     else if (mode == 1) gemm_tile<1>(ph, which, pm, pn);
;     else if (mode == 2) gemm_tile<2>(ph, which, pm, pn);
;     else gemm_tile<3>(ph, which, pm, pn);
.LBB0_88:
	s_lshl_b32 s4, s4, 3
	s_abs_i32 s7, s4
	v_cvt_f32_u32_e32 v0, s7
	s_sub_i32 s8, 0, s7
	s_abs_i32 s6, s2
	s_xor_b32 s5, s2, s4
	v_rcp_iflag_f32_e32 v0, v0
	s_ashr_i32 s5, s5, 31
	v_mul_f32_e32 v0, 0x4f7ffffe, v0
	v_cvt_u32_f32_e32 v0, v0
	s_nop 0
	v_readfirstlane_b32 s9, v0
	s_mul_i32 s8, s8, s9
	s_mul_hi_u32 s8, s9, s8
	s_add_i32 s9, s9, s8
	s_mul_hi_u32 s8, s6, s9
	s_mul_i32 s9, s8, s7
	s_sub_i32 s6, s6, s9
	s_add_i32 s9, s8, 1
	s_sub_i32 s10, s6, s7
	s_cmp_ge_u32 s6, s7
	s_cselect_b32 s8, s9, s8
	s_cselect_b32 s6, s10, s6
	s_add_i32 s9, s8, 1
	s_cmp_ge_u32 s6, s7
	s_cselect_b32 s6, s9, s8
	s_xor_b32 s6, s6, s5
	s_sub_i32 s5, s6, s5
	s_lshl_b32 s6, s5, 3
	s_sub_i32 s3, s3, s6
	s_min_i32 s3, s3, 8
	s_abs_i32 s7, s3
	v_cvt_f32_u32_e32 v0, s7
	s_sub_i32 s8, 0, s7
	s_mul_i32 s5, s5, s4
	s_sub_i32 s2, s2, s5
	v_rcp_iflag_f32_e32 v0, v0
	s_abs_i32 s5, s2
	s_xor_b32 s4, s2, s3
	s_ashr_i32 s4, s4, 31
	v_mul_f32_e32 v0, 0x4f7ffffe, v0
	v_cvt_u32_f32_e32 v0, v0
	s_nop 0
	v_readfirstlane_b32 s9, v0
	s_mul_i32 s8, s8, s9
	s_mul_hi_u32 s8, s9, s8
	s_add_i32 s9, s9, s8
	s_mul_hi_u32 s8, s5, s9
	s_mul_i32 s9, s8, s7
	s_sub_i32 s5, s5, s9
	s_add_i32 s9, s8, 1
	s_sub_i32 s10, s5, s7
	s_cmp_ge_u32 s5, s7
	s_cselect_b32 s8, s9, s8
	s_cselect_b32 s5, s10, s5
	s_add_i32 s9, s8, 1
	s_cmp_ge_u32 s5, s7
	s_cselect_b32 s5, s9, s8
	s_xor_b32 s5, s5, s4
	s_sub_i32 s74, s5, s4
	s_mul_i32 s3, s74, s3
	s_sub_i32 s31, s2, s3
	s_add_i32 s31, s31, s6
	s_mov_b64 s[4:5], -1
	s_mov_b64 s[8:9], 0
	s_cmp_lt_i32 s84, 1
	s_mov_b64 s[2:3], 0
	s_cbranch_scc1 .LBB0_98
	s_cmp_gt_i32 s84, 1
	s_cbranch_scc0 .LBB0_180
	s_cmp_eq_u32 s84, 2
	s_mov_b64 s[2:3], -1
	s_cbranch_scc0 .LBB0_179
	v_mov_b32_e32 v0, v208
	s_mov_b64 s[2:3], s[0:1]
	s_load_dwordx2 s[2:3], s[2:3], 0xf8
	s_mov_b64 s[24:25], -1
	s_mov_b64 s[10:11], 0
	s_mov_b64 s[20:21], 0
	s_mov_b64 s[22:23], 0
	s_waitcnt lgkmcnt(0)
	s_add_u32 s6, s2, 0x61a6000
	s_addc_u32 s7, s3, 0
	s_add_u32 s16, s2, 0xe1a6000
	s_addc_u32 s17, s3, 0
	s_cmp_lt_i32 s34, 5
	s_cbranch_scc1 .LBB0_109
	s_mov_b64 s[18:19], -1
	s_cmp_gt_i32 s34, 16
	s_cbranch_scc0 .LBB0_101
	s_cmp_gt_i32 s34, 18
	s_mov_b64 s[4:5], 0
	s_cbranch_scc0 .LBB0_95
	s_cmp_lt_i32 s34, 27
	s_mov_b64 s[18:19], 0
	s_mov_b64 s[20:21], -1
	s_cselect_b64 s[4:5], -1, 0

; template <int MODE>
; __device__ __forceinline__ void gemm_tile(const int ph, const int which, const int pm, const int pn) {
;     ...
;   for (int ai = 0; ai < 2; ++ai)
;     for (int m = 0; m < 4; ++m) {
;       const int row = browC + ai * HALF + wr * 64 + m * 16 + fr;
;       float s = 1.f;
;       if (MODE == 1) s = scale[row];
;       for (int bj = 0; bj < 2; ++bj) {
;         uint2 o[2];
; #pragma unroll
;         for (int n = 0; n < 2; ++n) {
;           const int col = ecol + bj * HALF + wc * 32 + n * 16 + fq * 4;
;           f32x4 v = acc[ai][bj][m][n];
;           float x0, x1, x2, x3;
;           if (MODE == 2) {
;             float4 c4 = *(const float4*)(scale + col);
;             x0 = v[0] * c4.x; x1 = v[1] * c4.y; x2 = v[2] * c4.z; x3 = v[3] * c4.w;
;           } else {
;             x0 = v[0] * s; x1 = v[1] * s; x2 = v[2] * s; x3 = v[3] * s;
;           }
;           if (MODE == 1 && act) { x0 = gelu_f(x0); x1 = gelu_f(x1); x2 = gelu_f(x2); x3 = gelu_f(x3); }
;           o[n].x = pack2(x0, x1);
;           o[n].y = pack2(x2, x3);
;         }
;         auto rx = __builtin_amdgcn_permlane16_swap(o[0].x, o[1].x, false, false);
;         auto ry = __builtin_amdgcn_permlane16_swap(o[0].y, o[1].y, false, false);
;         const int colw = ecol + bj * HALF + wc * 32 + (fq & 1) * 16 + (fq >> 1) * 8;
;         *(uint4*)(C + (size_t)row * ldc + colw) = make_uint4(rx[0], ry[0], rx[1], ry[1]);
;       }
.LBB0_178:
	v_lshlrev_b32_e32 v130, 2, v130
	v_and_b32_e32 v130, 8, v130
	v_add_u32_e32 v133, s24, v133
	v_lshlrev_b32_e32 v131, 5, v131
	v_lshlrev_b32_e32 v132, 2, v132
	v_and_or_b32 v0, v0, 16, v130
	v_or3_b32 v134, v131, v132, s23
	v_or3_b32 v138, v0, v131, s23
	v_mad_u64_u32 v[130:131], s[4:5], v133, s22, 0
	v_ashrrev_i32_e32 v132, 31, v133
	v_mov_b32_e32 v0, v131
	v_mad_u64_u32 v[136:137], s[4:5], v132, s22, v[0:1]
	v_mov_b32_e32 v131, v136
	v_ashrrev_i32_e32 v135, 31, v134
	v_lshl_add_u64 v[140:141], v[130:131], 1, s[2:3]
	v_lshl_add_u64 v[130:131], v[134:135], 2, s[10:11]
	global_load_dwordx4 v[160:163], v[130:131], off
	global_load_dwordx4 v[164:167], v[130:131], off offset:64
	global_load_dwordx4 v[168:171], v[130:131], off offset:512
	global_load_dwordx4 v[172:175], v[130:131], off offset:576
	v_ashrrev_i32_e32 v139, 31, v138
	v_add_u32_e32 v0, 16, v133
	s_waitcnt vmcnt(0)
	v_pk_mul_f32 v[126:127], v[126:127], v[160:161]
	v_pk_mul_f32 v[128:129], v[128:129], v[162:163]
	v_cvt_pk_bf16_f32 v126, v126, v127
	v_cvt_pk_bf16_f32 v127, v128, v129
	v_pk_mul_f32 v[122:123], v[122:123], v[164:165]
	v_pk_mul_f32 v[124:125], v[124:125], v[166:167]
	v_cvt_pk_bf16_f32 v128, v122, v123
	v_cvt_pk_bf16_f32 v129, v124, v125
	v_lshlrev_b64 v[122:123], 1, v[138:139]
	v_permlane16_swap_b32_e32 v126, v128
	v_permlane16_swap_b32_e32 v127, v129
	v_lshl_add_u64 v[134:135], v[140:141], 0, v[122:123]
	global_store_dwordx4 v[134:135], v[126:129], off
	v_pk_mul_f32 v[118:119], v[118:119], v[168:169]
	v_pk_mul_f32 v[120:121], v[120:121], v[170:171]
	v_cvt_pk_bf16_f32 v118, v118, v119
	v_cvt_pk_bf16_f32 v119, v120, v121
	v_pk_mul_f32 v[114:115], v[114:115], v[172:173]
	v_pk_mul_f32 v[116:117], v[116:117], v[174:175]
	v_cvt_pk_bf16_f32 v120, v114, v115
	v_mad_u64_u32 v[114:115], s[4:5], v0, s22, 0
	v_cvt_pk_bf16_f32 v121, v116, v117
	v_ashrrev_i32_e32 v116, 31, v0
	v_mov_b32_e32 v0, v115
	v_permlane16_swap_b32_e32 v118, v120
	v_permlane16_swap_b32_e32 v119, v121
	v_mad_u64_u32 v[116:117], s[4:5], v116, s22, v[0:1]
	global_store_dwordx4 v[134:135], v[118:121], off offset:256
	v_mov_b32_e32 v115, v116
	v_add_u32_e32 v0, 32, v133
	v_lshl_add_u64 v[118:119], v[114:115], 1, s[2:3]
	v_pk_mul_f32 v[110:111], v[110:111], v[160:161]
	v_pk_mul_f32 v[112:113], v[112:113], v[162:163]
	v_cvt_pk_bf16_f32 v110, v110, v111
	v_cvt_pk_bf16_f32 v111, v112, v113
	v_pk_mul_f32 v[106:107], v[106:107], v[164:165]
	v_pk_mul_f32 v[108:109], v[108:109], v[166:167]
	v_cvt_pk_bf16_f32 v112, v106, v107
	v_cvt_pk_bf16_f32 v113, v108, v109
	s_nop 0
	v_permlane16_swap_b32_e32 v110, v112
	v_permlane16_swap_b32_e32 v111, v113
	v_lshl_add_u64 v[114:115], v[118:119], 0, v[122:123]
	global_store_dwordx4 v[114:115], v[110:113], off
	v_pk_mul_f32 v[102:103], v[102:103], v[168:169]
	v_pk_mul_f32 v[104:105], v[104:105], v[170:171]
	v_cvt_pk_bf16_f32 v102, v102, v103
	v_cvt_pk_bf16_f32 v103, v104, v105
	v_pk_mul_f32 v[98:99], v[98:99], v[172:173]
	v_pk_mul_f32 v[100:101], v[100:101], v[174:175]
	v_cvt_pk_bf16_f32 v104, v98, v99
	v_mad_u64_u32 v[98:99], s[4:5], v0, s22, 0
	v_cvt_pk_bf16_f32 v105, v100, v101
	v_ashrrev_i32_e32 v100, 31, v0
	v_mov_b32_e32 v0, v99
	v_permlane16_swap_b32_e32 v102, v104
	v_permlane16_swap_b32_e32 v103, v105
	v_mad_u64_u32 v[100:101], s[4:5], v100, s22, v[0:1]
	global_store_dwordx4 v[114:115], v[102:105], off offset:256
	v_mov_b32_e32 v99, v100
	v_add_u32_e32 v0, 48, v133
	v_lshl_add_u64 v[102:103], v[98:99], 1, s[2:3]
	v_pk_mul_f32 v[94:95], v[94:95], v[160:161]
	v_pk_mul_f32 v[96:97], v[96:97], v[162:163]
	v_cvt_pk_bf16_f32 v94, v94, v95
	v_cvt_pk_bf16_f32 v95, v96, v97
	v_pk_mul_f32 v[90:91], v[90:91], v[164:165]
	v_pk_mul_f32 v[92:93], v[92:93], v[166:167]
	v_cvt_pk_bf16_f32 v96, v90, v91
	v_cvt_pk_bf16_f32 v97, v92, v93
	s_nop 0
	v_permlane16_swap_b32_e32 v94, v96
	v_permlane16_swap_b32_e32 v95, v97
	v_lshl_add_u64 v[98:99], v[102:103], 0, v[122:123]
	global_store_dwordx4 v[98:99], v[94:97], off
	v_pk_mul_f32 v[86:87], v[86:87], v[168:169]
	v_pk_mul_f32 v[88:89], v[88:89], v[170:171]
	v_cvt_pk_bf16_f32 v86, v86, v87
	v_cvt_pk_bf16_f32 v87, v88, v89
	v_pk_mul_f32 v[82:83], v[82:83], v[172:173]
	v_pk_mul_f32 v[84:85], v[84:85], v[174:175]
	v_cvt_pk_bf16_f32 v88, v82, v83
	v_mad_u64_u32 v[82:83], s[4:5], v0, s22, 0
	v_cvt_pk_bf16_f32 v89, v84, v85
	v_ashrrev_i32_e32 v84, 31, v0
	v_mov_b32_e32 v0, v83
	v_permlane16_swap_b32_e32 v86, v88
	v_permlane16_swap_b32_e32 v87, v89
	v_mad_u64_u32 v[84:85], s[4:5], v84, s22, v[0:1]
	global_store_dwordx4 v[98:99], v[86:89], off offset:256
	v_mov_b32_e32 v83, v84
	v_add_u32_e32 v0, 0x80, v133
	v_lshl_add_u64 v[86:87], v[82:83], 1, s[2:3]
	v_pk_mul_f32 v[78:79], v[78:79], v[160:161]
	v_pk_mul_f32 v[80:81], v[80:81], v[162:163]
	v_cvt_pk_bf16_f32 v78, v78, v79
	v_cvt_pk_bf16_f32 v79, v80, v81
	v_pk_mul_f32 v[74:75], v[74:75], v[164:165]
	v_pk_mul_f32 v[76:77], v[76:77], v[166:167]
	v_cvt_pk_bf16_f32 v80, v74, v75
	v_cvt_pk_bf16_f32 v81, v76, v77
	s_nop 0
	v_permlane16_swap_b32_e32 v78, v80
	v_permlane16_swap_b32_e32 v79, v81
	v_lshl_add_u64 v[82:83], v[86:87], 0, v[122:123]
	global_store_dwordx4 v[82:83], v[78:81], off
; template <int MODE>
; __device__ __forceinline__ void gemm_tile(const int ph, const int which, const int pm, const int pn) {
;     ...
;   for (int ai = 0; ai < 2; ++ai)
;     for (int m = 0; m < 4; ++m) {
;       const int row = browC + ai * HALF + wr * 64 + m * 16 + fr;
;       float s = 1.f;
;       if (MODE == 1) s = scale[row];
;       for (int bj = 0; bj < 2; ++bj) {
;         uint2 o[2];
; #pragma unroll
;         for (int n = 0; n < 2; ++n) {
;           const int col = ecol + bj * HALF + wc * 32 + n * 16 + fq * 4;
;           f32x4 v = acc[ai][bj][m][n];
;           float x0, x1, x2, x3;
;           if (MODE == 2) {
;             float4 c4 = *(const float4*)(scale + col);
;             x0 = v[0] * c4.x; x1 = v[1] * c4.y; x2 = v[2] * c4.z; x3 = v[3] * c4.w;
;           } else {
;             x0 = v[0] * s; x1 = v[1] * s; x2 = v[2] * s; x3 = v[3] * s;
;           }
;           if (MODE == 1 && act) { x0 = gelu_f(x0); x1 = gelu_f(x1); x2 = gelu_f(x2); x3 = gelu_f(x3); }
;           o[n].x = pack2(x0, x1);
;           o[n].y = pack2(x2, x3);
;         }
;         auto rx = __builtin_amdgcn_permlane16_swap(o[0].x, o[1].x, false, false);
;         auto ry = __builtin_amdgcn_permlane16_swap(o[0].y, o[1].y, false, false);
;         const int colw = ecol + bj * HALF + wc * 32 + (fq & 1) * 16 + (fq >> 1) * 8;
;         *(uint4*)(C + (size_t)row * ldc + colw) = make_uint4(rx[0], ry[0], rx[1], ry[1]);
;       }
	v_pk_mul_f32 v[70:71], v[70:71], v[168:169]
	v_pk_mul_f32 v[72:73], v[72:73], v[170:171]
	v_cvt_pk_bf16_f32 v70, v70, v71
	v_cvt_pk_bf16_f32 v71, v72, v73
	v_pk_mul_f32 v[66:67], v[66:67], v[172:173]
	v_pk_mul_f32 v[68:69], v[68:69], v[174:175]
	v_cvt_pk_bf16_f32 v72, v66, v67
	v_mad_u64_u32 v[66:67], s[4:5], v0, s22, 0
	v_cvt_pk_bf16_f32 v73, v68, v69
	v_ashrrev_i32_e32 v68, 31, v0
	v_mov_b32_e32 v0, v67
	v_permlane16_swap_b32_e32 v70, v72
	v_permlane16_swap_b32_e32 v71, v73
	v_mad_u64_u32 v[68:69], s[4:5], v68, s22, v[0:1]
	global_store_dwordx4 v[82:83], v[70:73], off offset:256
	v_mov_b32_e32 v67, v68
	v_add_u32_e32 v0, 0x90, v133
	v_lshl_add_u64 v[70:71], v[66:67], 1, s[2:3]
	v_pk_mul_f32 v[62:63], v[62:63], v[160:161]
	v_pk_mul_f32 v[64:65], v[64:65], v[162:163]
	v_cvt_pk_bf16_f32 v62, v62, v63
	v_cvt_pk_bf16_f32 v63, v64, v65
	v_pk_mul_f32 v[58:59], v[58:59], v[164:165]
	v_pk_mul_f32 v[60:61], v[60:61], v[166:167]
	v_cvt_pk_bf16_f32 v64, v58, v59
	v_cvt_pk_bf16_f32 v65, v60, v61
	s_nop 0
	v_permlane16_swap_b32_e32 v62, v64
	v_permlane16_swap_b32_e32 v63, v65
	v_lshl_add_u64 v[66:67], v[70:71], 0, v[122:123]
	global_store_dwordx4 v[66:67], v[62:65], off
	v_pk_mul_f32 v[54:55], v[54:55], v[168:169]
	v_pk_mul_f32 v[56:57], v[56:57], v[170:171]
	v_cvt_pk_bf16_f32 v54, v54, v55
	v_cvt_pk_bf16_f32 v55, v56, v57
	v_pk_mul_f32 v[50:51], v[50:51], v[172:173]
	v_pk_mul_f32 v[52:53], v[52:53], v[174:175]
	v_cvt_pk_bf16_f32 v56, v50, v51
	v_mad_u64_u32 v[50:51], s[4:5], v0, s22, 0
	v_cvt_pk_bf16_f32 v57, v52, v53
	v_ashrrev_i32_e32 v52, 31, v0
	v_mov_b32_e32 v0, v51
	v_permlane16_swap_b32_e32 v54, v56
	v_permlane16_swap_b32_e32 v55, v57
	v_mad_u64_u32 v[52:53], s[4:5], v52, s22, v[0:1]
	global_store_dwordx4 v[66:67], v[54:57], off offset:256
	v_mov_b32_e32 v51, v52
	v_add_u32_e32 v0, 0xa0, v133
	v_lshl_add_u64 v[54:55], v[50:51], 1, s[2:3]
	v_pk_mul_f32 v[46:47], v[46:47], v[160:161]
	v_pk_mul_f32 v[48:49], v[48:49], v[162:163]
	v_cvt_pk_bf16_f32 v46, v46, v47
	v_cvt_pk_bf16_f32 v47, v48, v49
	v_pk_mul_f32 v[42:43], v[42:43], v[164:165]
	v_pk_mul_f32 v[44:45], v[44:45], v[166:167]
	v_cvt_pk_bf16_f32 v48, v42, v43
	v_cvt_pk_bf16_f32 v49, v44, v45
	s_nop 0
	v_permlane16_swap_b32_e32 v46, v48
	v_permlane16_swap_b32_e32 v47, v49
	v_lshl_add_u64 v[50:51], v[54:55], 0, v[122:123]
	global_store_dwordx4 v[50:51], v[46:49], off
	v_pk_mul_f32 v[38:39], v[38:39], v[168:169]
	v_pk_mul_f32 v[40:41], v[40:41], v[170:171]
	v_cvt_pk_bf16_f32 v38, v38, v39
	v_cvt_pk_bf16_f32 v39, v40, v41
	v_pk_mul_f32 v[34:35], v[34:35], v[172:173]
	v_pk_mul_f32 v[36:37], v[36:37], v[174:175]
	v_cvt_pk_bf16_f32 v40, v34, v35
	v_mad_u64_u32 v[34:35], s[4:5], v0, s22, 0
	v_cvt_pk_bf16_f32 v41, v36, v37
	v_ashrrev_i32_e32 v36, 31, v0
	v_mov_b32_e32 v0, v35
	v_permlane16_swap_b32_e32 v38, v40
	v_permlane16_swap_b32_e32 v39, v41
	v_mad_u64_u32 v[36:37], s[4:5], v36, s22, v[0:1]
	global_store_dwordx4 v[50:51], v[38:41], off offset:256
	v_mov_b32_e32 v35, v36
	v_add_u32_e32 v0, 0xb0, v133
	v_lshl_add_u64 v[38:39], v[34:35], 1, s[2:3]
	v_pk_mul_f32 v[30:31], v[30:31], v[160:161]
	v_pk_mul_f32 v[32:33], v[32:33], v[162:163]
	v_cvt_pk_bf16_f32 v30, v30, v31
	v_cvt_pk_bf16_f32 v31, v32, v33
	v_pk_mul_f32 v[26:27], v[26:27], v[164:165]
	v_pk_mul_f32 v[28:29], v[28:29], v[166:167]
	v_cvt_pk_bf16_f32 v32, v26, v27
	v_cvt_pk_bf16_f32 v33, v28, v29
	s_nop 0
	v_permlane16_swap_b32_e32 v30, v32
	v_permlane16_swap_b32_e32 v31, v33
	v_lshl_add_u64 v[34:35], v[38:39], 0, v[122:123]
	global_store_dwordx4 v[34:35], v[30:33], off
	v_pk_mul_f32 v[22:23], v[22:23], v[168:169]
	v_pk_mul_f32 v[24:25], v[24:25], v[170:171]
	v_cvt_pk_bf16_f32 v22, v22, v23
	v_cvt_pk_bf16_f32 v23, v24, v25
	v_pk_mul_f32 v[18:19], v[18:19], v[172:173]
	v_pk_mul_f32 v[20:21], v[20:21], v[174:175]
	v_cvt_pk_bf16_f32 v24, v18, v19
	v_mad_u64_u32 v[18:19], s[4:5], v0, s22, 0
	v_cvt_pk_bf16_f32 v25, v20, v21
	v_ashrrev_i32_e32 v20, 31, v0
	v_mov_b32_e32 v0, v19
	v_permlane16_swap_b32_e32 v22, v24
	v_permlane16_swap_b32_e32 v23, v25
	v_mad_u64_u32 v[20:21], s[4:5], v20, s22, v[0:1]
	global_store_dwordx4 v[34:35], v[22:25], off offset:256
	v_mov_b32_e32 v19, v20
	s_nop 0
	v_lshl_add_u64 v[22:23], v[18:19], 1, s[2:3]
	s_mov_b64 s[2:3], 0
	v_pk_mul_f32 v[14:15], v[14:15], v[160:161]
	v_pk_mul_f32 v[16:17], v[16:17], v[162:163]
	v_cvt_pk_bf16_f32 v14, v14, v15
	v_cvt_pk_bf16_f32 v15, v16, v17
	v_pk_mul_f32 v[10:11], v[10:11], v[164:165]
	v_pk_mul_f32 v[12:13], v[12:13], v[166:167]
	v_cvt_pk_bf16_f32 v16, v10, v11
	v_cvt_pk_bf16_f32 v17, v12, v13
	s_nop 0
	v_permlane16_swap_b32_e32 v14, v16
	v_permlane16_swap_b32_e32 v15, v17
	v_lshl_add_u64 v[18:19], v[22:23], 0, v[122:123]
	global_store_dwordx4 v[18:19], v[14:17], off
	v_pk_mul_f32 v[6:7], v[6:7], v[168:169]
	v_pk_mul_f32 v[8:9], v[8:9], v[170:171]
	v_cvt_pk_bf16_f32 v6, v6, v7
	v_cvt_pk_bf16_f32 v7, v8, v9
	v_pk_mul_f32 v[2:3], v[2:3], v[172:173]
	v_pk_mul_f32 v[4:5], v[4:5], v[174:175]
	v_cvt_pk_bf16_f32 v8, v2, v3
	v_cvt_pk_bf16_f32 v9, v4, v5
	s_nop 0
	v_permlane16_swap_b32_e32 v6, v8
	v_permlane16_swap_b32_e32 v7, v9
	global_store_dwordx4 v[18:19], v[6:9], off offset:256

; template <int MODE>
; __device__ __forceinline__ void gemm_tile(const int ph, const int which, const int pm, const int pn) {
;     ...
;   for (int ai = 0; ai < 2; ++ai)
;     for (int m = 0; m < 4; ++m) {
;       const int row = browC + ai * HALF + wr * 64 + m * 16 + fr;
;       float s = 1.f;
;       if (MODE == 1) s = scale[row];
;       for (int bj = 0; bj < 2; ++bj) {
;         uint2 o[2];
; #pragma unroll
;         for (int n = 0; n < 2; ++n) {
;           const int col = ecol + bj * HALF + wc * 32 + n * 16 + fq * 4;
;           f32x4 v = acc[ai][bj][m][n];
;           float x0, x1, x2, x3;
;           if (MODE == 2) {
;             float4 c4 = *(const float4*)(scale + col);
;             x0 = v[0] * c4.x; x1 = v[1] * c4.y; x2 = v[2] * c4.z; x3 = v[3] * c4.w;
;           } else {
;             x0 = v[0] * s; x1 = v[1] * s; x2 = v[2] * s; x3 = v[3] * s;
;           }
;           if (MODE == 1 && act) { x0 = gelu_f(x0); x1 = gelu_f(x1); x2 = gelu_f(x2); x3 = gelu_f(x3); }
.LBB0_266:
	v_add_u32_e32 v130, s26, v130
	v_ashrrev_i32_e32 v131, 31, v130
	v_lshl_add_u64 v[132:133], v[130:131], 2, s[16:17]
	global_load_dword v176, v[132:133], off
	global_load_dword v177, v[132:133], off offset:64
	global_load_dword v178, v[132:133], off offset:128
	global_load_dword v179, v[132:133], off offset:192
	global_load_dword v180, v[132:133], off offset:512
	global_load_dword v181, v[132:133], off offset:576
	global_load_dword v182, v[132:133], off offset:640
	global_load_dword v183, v[132:133], off offset:704
	s_and_b64 vcc, exec, s[10:11]
	s_waitcnt vmcnt(0)
	v_mov_b32_e32 v134, v176
	v_pk_mul_f32 v[126:127], v[126:127], v[134:135] op_sel_hi:[1,0]
	v_pk_mul_f32 v[128:129], v[128:129], v[134:135] op_sel_hi:[1,0]
	s_cbranch_vccnz .LBB0_268
	v_pk_mul_f32 v[136:137], v[126:127], v[126:127]
	s_nop 0
	v_fmamk_f32 v135, v136, 0x3dd2d3e7, v209
	v_mul_f32_e64 v135, v135, -v126
	v_exp_f32_e32 v135, v135
	s_nop 0
	v_add_f32_e32 v135, 1.0, v135
	v_rcp_f32_e32 v136, v135
	v_fmamk_f32 v135, v137, 0x3dd2d3e7, v209
	v_mul_f32_e64 v135, v135, -v127
	v_exp_f32_e32 v135, v135
	s_nop 0
	v_add_f32_e32 v135, 1.0, v135
	v_rcp_f32_e32 v137, v135
	s_nop 0
	v_pk_mul_f32 v[126:127], v[126:127], v[136:137]
	v_pk_mul_f32 v[136:137], v[128:129], v[128:129]
	s_nop 0
	v_fmamk_f32 v135, v136, 0x3dd2d3e7, v209
	v_mul_f32_e64 v135, v135, -v128
	v_exp_f32_e32 v135, v135
	s_nop 0
	v_add_f32_e32 v135, 1.0, v135
	v_rcp_f32_e32 v136, v135
	v_fmamk_f32 v135, v137, 0x3dd2d3e7, v209
	v_mul_f32_e64 v135, v135, -v129
	v_exp_f32_e32 v135, v135
	s_nop 0
	v_add_f32_e32 v135, 1.0, v135
	v_rcp_f32_e32 v137, v135
	s_nop 0
	v_pk_mul_f32 v[128:129], v[128:129], v[136:137]

; template <int MODE>
; __device__ __forceinline__ void gemm_tile(const int ph, const int which, const int pm, const int pn) {
;     ...
;   for (int ai = 0; ai < 2; ++ai)
;     for (int m = 0; m < 4; ++m) {
;       const int row = browC + ai * HALF + wr * 64 + m * 16 + fr;
;       float s = 1.f;
;       if (MODE == 1) s = scale[row];
;       for (int bj = 0; bj < 2; ++bj) {
;         uint2 o[2];
; #pragma unroll
;         for (int n = 0; n < 2; ++n) {
;           const int col = ecol + bj * HALF + wc * 32 + n * 16 + fq * 4;
;           f32x4 v = acc[ai][bj][m][n];
;           float x0, x1, x2, x3;
;           if (MODE == 2) {
;             float4 c4 = *(const float4*)(scale + col);
;             x0 = v[0] * c4.x; x1 = v[1] * c4.y; x2 = v[2] * c4.z; x3 = v[3] * c4.w;
;           } else {
;             x0 = v[0] * s; x1 = v[1] * s; x2 = v[2] * s; x3 = v[3] * s;
;           }
;           if (MODE == 1 && act) { x0 = gelu_f(x0); x1 = gelu_f(x1); x2 = gelu_f(x2); x3 = gelu_f(x3); }
;           o[n].x = pack2(x0, x1);
;           o[n].y = pack2(x2, x3);
;         }
;         auto rx = __builtin_amdgcn_permlane16_swap(o[0].x, o[1].x, false, false);
;         auto ry = __builtin_amdgcn_permlane16_swap(o[0].y, o[1].y, false, false);
;         const int colw = ecol + bj * HALF + wc * 32 + (fq & 1) * 16 + (fq >> 1) * 8;
;         *(uint4*)(C + (size_t)row * ldc + colw) = make_uint4(rx[0], ry[0], rx[1], ry[1]);
.LBB0_274:
	v_cvt_pk_bf16_f32 v118, v118, v119
	v_cvt_pk_bf16_f32 v119, v120, v121
	v_cvt_pk_bf16_f32 v120, v114, v115
	v_cvt_pk_bf16_f32 v121, v116, v117
	s_nop 0
	v_permlane16_swap_b32_e32 v118, v120
	v_permlane16_swap_b32_e32 v119, v121
	global_store_dwordx4 v[124:125], v[118:121], off offset:256
	s_and_b64 vcc, exec, s[4:5]
	v_mov_b32_e32 v114, v177
	v_pk_mul_f32 v[110:111], v[110:111], v[114:115] op_sel_hi:[1,0]
	v_pk_mul_f32 v[112:113], v[112:113], v[114:115] op_sel_hi:[1,0]
	s_cbranch_vccnz .LBB0_276
	v_pk_mul_f32 v[116:117], v[110:111], v[110:111]
	s_nop 0
	v_fmamk_f32 v0, v116, 0x3dd2d3e7, v209
	v_mul_f32_e64 v0, v0, -v110
	v_exp_f32_e32 v0, v0
	s_nop 0
	v_add_f32_e32 v0, 1.0, v0
	v_rcp_f32_e32 v116, v0
	v_fmamk_f32 v0, v117, 0x3dd2d3e7, v209
	v_mul_f32_e64 v0, v0, -v111
	v_exp_f32_e32 v0, v0
	s_nop 0
	v_add_f32_e32 v0, 1.0, v0
	v_rcp_f32_e32 v117, v0
	s_nop 0
	v_pk_mul_f32 v[110:111], v[110:111], v[116:117]
	v_pk_mul_f32 v[116:117], v[112:113], v[112:113]
	s_nop 0
	v_fmamk_f32 v0, v116, 0x3dd2d3e7, v209
	v_mul_f32_e64 v0, v0, -v112
	v_exp_f32_e32 v0, v0
	s_nop 0
	v_add_f32_e32 v0, 1.0, v0
	v_rcp_f32_e32 v116, v0
	v_fmamk_f32 v0, v117, 0x3dd2d3e7, v209
	v_mul_f32_e64 v0, v0, -v113
	v_exp_f32_e32 v0, v0
	s_nop 0
	v_add_f32_e32 v0, 1.0, v0
	v_rcp_f32_e32 v117, v0
	s_nop 0
	v_pk_mul_f32 v[112:113], v[112:113], v[116:117]

; template <int MODE>
; __device__ __forceinline__ void gemm_tile(const int ph, const int which, const int pm, const int pn) {
;     ...
;   for (int ai = 0; ai < 2; ++ai)
;     for (int m = 0; m < 4; ++m) {
;       const int row = browC + ai * HALF + wr * 64 + m * 16 + fr;
;       float s = 1.f;
;       if (MODE == 1) s = scale[row];
;       for (int bj = 0; bj < 2; ++bj) {
;         uint2 o[2];
; #pragma unroll
;         for (int n = 0; n < 2; ++n) {
;           const int col = ecol + bj * HALF + wc * 32 + n * 16 + fq * 4;
;           f32x4 v = acc[ai][bj][m][n];
;           float x0, x1, x2, x3;
;           if (MODE == 2) {
;             float4 c4 = *(const float4*)(scale + col);
;             x0 = v[0] * c4.x; x1 = v[1] * c4.y; x2 = v[2] * c4.z; x3 = v[3] * c4.w;
;           } else {
;             x0 = v[0] * s; x1 = v[1] * s; x2 = v[2] * s; x3 = v[3] * s;
;           }
;           if (MODE == 1 && act) { x0 = gelu_f(x0); x1 = gelu_f(x1); x2 = gelu_f(x2); x3 = gelu_f(x3); }
;           o[n].x = pack2(x0, x1);
;           o[n].y = pack2(x2, x3);
;         }
;         auto rx = __builtin_amdgcn_permlane16_swap(o[0].x, o[1].x, false, false);
;         auto ry = __builtin_amdgcn_permlane16_swap(o[0].y, o[1].y, false, false);
;         const int colw = ecol + bj * HALF + wc * 32 + (fq & 1) * 16 + (fq >> 1) * 8;
;         *(uint4*)(C + (size_t)row * ldc + colw) = make_uint4(rx[0], ry[0], rx[1], ry[1]);
.LBB0_282:
	v_cvt_pk_bf16_f32 v102, v102, v103
	v_cvt_pk_bf16_f32 v103, v104, v105
	v_cvt_pk_bf16_f32 v104, v98, v99
	v_cvt_pk_bf16_f32 v105, v100, v101
	s_nop 0
	v_permlane16_swap_b32_e32 v102, v104
	v_permlane16_swap_b32_e32 v103, v105
	global_store_dwordx4 v[106:107], v[102:105], off offset:256
	s_and_b64 vcc, exec, s[4:5]
	v_mov_b32_e32 v98, v178
	v_pk_mul_f32 v[94:95], v[94:95], v[98:99] op_sel_hi:[1,0]
	v_pk_mul_f32 v[96:97], v[96:97], v[98:99] op_sel_hi:[1,0]
	s_cbranch_vccnz .LBB0_284
	v_pk_mul_f32 v[100:101], v[94:95], v[94:95]
	s_nop 0
	v_fmamk_f32 v0, v100, 0x3dd2d3e7, v209
	v_mul_f32_e64 v0, v0, -v94
	v_exp_f32_e32 v0, v0
	s_nop 0
	v_add_f32_e32 v0, 1.0, v0
	v_rcp_f32_e32 v100, v0
	v_fmamk_f32 v0, v101, 0x3dd2d3e7, v209
	v_mul_f32_e64 v0, v0, -v95
	v_exp_f32_e32 v0, v0
	s_nop 0
	v_add_f32_e32 v0, 1.0, v0
	v_rcp_f32_e32 v101, v0
	s_nop 0
	v_pk_mul_f32 v[94:95], v[94:95], v[100:101]
	v_pk_mul_f32 v[100:101], v[96:97], v[96:97]
	s_nop 0
	v_fmamk_f32 v0, v100, 0x3dd2d3e7, v209
	v_mul_f32_e64 v0, v0, -v96
	v_exp_f32_e32 v0, v0
	s_nop 0
	v_add_f32_e32 v0, 1.0, v0
	v_rcp_f32_e32 v100, v0
	v_fmamk_f32 v0, v101, 0x3dd2d3e7, v209
	v_mul_f32_e64 v0, v0, -v97
	v_exp_f32_e32 v0, v0
	s_nop 0
	v_add_f32_e32 v0, 1.0, v0
	v_rcp_f32_e32 v101, v0
	s_nop 0
	v_pk_mul_f32 v[96:97], v[96:97], v[100:101]

; template <int MODE>
; __device__ __forceinline__ void gemm_tile(const int ph, const int which, const int pm, const int pn) {
;     ...
;   for (int ai = 0; ai < 2; ++ai)
;     for (int m = 0; m < 4; ++m) {
;       const int row = browC + ai * HALF + wr * 64 + m * 16 + fr;
;       float s = 1.f;
;       if (MODE == 1) s = scale[row];
;       for (int bj = 0; bj < 2; ++bj) {
;         uint2 o[2];
; #pragma unroll
;         for (int n = 0; n < 2; ++n) {
;           const int col = ecol + bj * HALF + wc * 32 + n * 16 + fq * 4;
;           f32x4 v = acc[ai][bj][m][n];
;           float x0, x1, x2, x3;
;           if (MODE == 2) {
;             float4 c4 = *(const float4*)(scale + col);
;             x0 = v[0] * c4.x; x1 = v[1] * c4.y; x2 = v[2] * c4.z; x3 = v[3] * c4.w;
;           } else {
;             x0 = v[0] * s; x1 = v[1] * s; x2 = v[2] * s; x3 = v[3] * s;
;           }
;           if (MODE == 1 && act) { x0 = gelu_f(x0); x1 = gelu_f(x1); x2 = gelu_f(x2); x3 = gelu_f(x3); }
;           o[n].x = pack2(x0, x1);
;           o[n].y = pack2(x2, x3);
;         }
;         auto rx = __builtin_amdgcn_permlane16_swap(o[0].x, o[1].x, false, false);
;         auto ry = __builtin_amdgcn_permlane16_swap(o[0].y, o[1].y, false, false);
;         const int colw = ecol + bj * HALF + wc * 32 + (fq & 1) * 16 + (fq >> 1) * 8;
;         *(uint4*)(C + (size_t)row * ldc + colw) = make_uint4(rx[0], ry[0], rx[1], ry[1]);
.LBB0_290:
	v_cvt_pk_bf16_f32 v86, v86, v87
	v_cvt_pk_bf16_f32 v87, v88, v89
	v_cvt_pk_bf16_f32 v88, v82, v83
	v_cvt_pk_bf16_f32 v89, v84, v85
	s_nop 0
	v_permlane16_swap_b32_e32 v86, v88
	v_permlane16_swap_b32_e32 v87, v89
	global_store_dwordx4 v[90:91], v[86:89], off offset:256
	s_and_b64 vcc, exec, s[4:5]
	v_mov_b32_e32 v82, v179
	v_pk_mul_f32 v[78:79], v[78:79], v[82:83] op_sel_hi:[1,0]
	v_pk_mul_f32 v[80:81], v[80:81], v[82:83] op_sel_hi:[1,0]
	s_cbranch_vccnz .LBB0_292
	v_pk_mul_f32 v[84:85], v[78:79], v[78:79]
	s_nop 0
	v_fmamk_f32 v0, v84, 0x3dd2d3e7, v209
	v_mul_f32_e64 v0, v0, -v78
	v_exp_f32_e32 v0, v0
	s_nop 0
	v_add_f32_e32 v0, 1.0, v0
	v_rcp_f32_e32 v84, v0
	v_fmamk_f32 v0, v85, 0x3dd2d3e7, v209
	v_mul_f32_e64 v0, v0, -v79
	v_exp_f32_e32 v0, v0
	s_nop 0
	v_add_f32_e32 v0, 1.0, v0
	v_rcp_f32_e32 v85, v0
	s_nop 0
	v_pk_mul_f32 v[78:79], v[78:79], v[84:85]
	v_pk_mul_f32 v[84:85], v[80:81], v[80:81]
	s_nop 0
	v_fmamk_f32 v0, v84, 0x3dd2d3e7, v209
	v_mul_f32_e64 v0, v0, -v80
	v_exp_f32_e32 v0, v0
	s_nop 0
	v_add_f32_e32 v0, 1.0, v0
	v_rcp_f32_e32 v84, v0
	v_fmamk_f32 v0, v85, 0x3dd2d3e7, v209
	v_mul_f32_e64 v0, v0, -v81
	v_exp_f32_e32 v0, v0
	s_nop 0
	v_add_f32_e32 v0, 1.0, v0
	v_rcp_f32_e32 v85, v0
	s_nop 0
	v_pk_mul_f32 v[80:81], v[80:81], v[84:85]

; template <int MODE>
; __device__ __forceinline__ void gemm_tile(const int ph, const int which, const int pm, const int pn) {
;     ...
;   for (int ai = 0; ai < 2; ++ai)
;     for (int m = 0; m < 4; ++m) {
;       const int row = browC + ai * HALF + wr * 64 + m * 16 + fr;
;       float s = 1.f;
;       if (MODE == 1) s = scale[row];
;       for (int bj = 0; bj < 2; ++bj) {
;         uint2 o[2];
; #pragma unroll
;         for (int n = 0; n < 2; ++n) {
;           const int col = ecol + bj * HALF + wc * 32 + n * 16 + fq * 4;
;           f32x4 v = acc[ai][bj][m][n];
;           float x0, x1, x2, x3;
;           if (MODE == 2) {
;             float4 c4 = *(const float4*)(scale + col);
;             x0 = v[0] * c4.x; x1 = v[1] * c4.y; x2 = v[2] * c4.z; x3 = v[3] * c4.w;
;           } else {
;             x0 = v[0] * s; x1 = v[1] * s; x2 = v[2] * s; x3 = v[3] * s;
;           }
;           if (MODE == 1 && act) { x0 = gelu_f(x0); x1 = gelu_f(x1); x2 = gelu_f(x2); x3 = gelu_f(x3); }
;           o[n].x = pack2(x0, x1);
;           o[n].y = pack2(x2, x3);
;         }
;         auto rx = __builtin_amdgcn_permlane16_swap(o[0].x, o[1].x, false, false);
;         auto ry = __builtin_amdgcn_permlane16_swap(o[0].y, o[1].y, false, false);
;         const int colw = ecol + bj * HALF + wc * 32 + (fq & 1) * 16 + (fq >> 1) * 8;
;         *(uint4*)(C + (size_t)row * ldc + colw) = make_uint4(rx[0], ry[0], rx[1], ry[1]);
.LBB0_298:
	v_cvt_pk_bf16_f32 v70, v70, v71
	v_cvt_pk_bf16_f32 v71, v72, v73
	v_cvt_pk_bf16_f32 v72, v66, v67
	v_cvt_pk_bf16_f32 v73, v68, v69
	s_nop 0
	v_permlane16_swap_b32_e32 v70, v72
	v_permlane16_swap_b32_e32 v71, v73
	global_store_dwordx4 v[74:75], v[70:73], off offset:256
	s_and_b64 vcc, exec, s[4:5]
	v_mov_b32_e32 v66, v180
	v_pk_mul_f32 v[62:63], v[62:63], v[66:67] op_sel_hi:[1,0]
	v_pk_mul_f32 v[64:65], v[64:65], v[66:67] op_sel_hi:[1,0]
	s_cbranch_vccnz .LBB0_300
	v_pk_mul_f32 v[68:69], v[62:63], v[62:63]
	s_nop 0
	v_fmamk_f32 v0, v68, 0x3dd2d3e7, v209
	v_mul_f32_e64 v0, v0, -v62
	v_exp_f32_e32 v0, v0
	s_nop 0
	v_add_f32_e32 v0, 1.0, v0
	v_rcp_f32_e32 v68, v0
	v_fmamk_f32 v0, v69, 0x3dd2d3e7, v209
	v_mul_f32_e64 v0, v0, -v63
	v_exp_f32_e32 v0, v0
	s_nop 0
	v_add_f32_e32 v0, 1.0, v0
	v_rcp_f32_e32 v69, v0
	s_nop 0
	v_pk_mul_f32 v[62:63], v[62:63], v[68:69]
	v_pk_mul_f32 v[68:69], v[64:65], v[64:65]
	s_nop 0
	v_fmamk_f32 v0, v68, 0x3dd2d3e7, v209
	v_mul_f32_e64 v0, v0, -v64
	v_exp_f32_e32 v0, v0
	s_nop 0
	v_add_f32_e32 v0, 1.0, v0
	v_rcp_f32_e32 v68, v0
	v_fmamk_f32 v0, v69, 0x3dd2d3e7, v209
	v_mul_f32_e64 v0, v0, -v65
	v_exp_f32_e32 v0, v0
	s_nop 0
	v_add_f32_e32 v0, 1.0, v0
	v_rcp_f32_e32 v69, v0
	s_nop 0
	v_pk_mul_f32 v[64:65], v[64:65], v[68:69]

; template <int MODE>
; __device__ __forceinline__ void gemm_tile(const int ph, const int which, const int pm, const int pn) {
;     ...
;   for (int ai = 0; ai < 2; ++ai)
;     for (int m = 0; m < 4; ++m) {
;       const int row = browC + ai * HALF + wr * 64 + m * 16 + fr;
;       float s = 1.f;
;       if (MODE == 1) s = scale[row];
;       for (int bj = 0; bj < 2; ++bj) {
;         uint2 o[2];
; #pragma unroll
;         for (int n = 0; n < 2; ++n) {
;           const int col = ecol + bj * HALF + wc * 32 + n * 16 + fq * 4;
;           f32x4 v = acc[ai][bj][m][n];
;           float x0, x1, x2, x3;
;           if (MODE == 2) {
;             float4 c4 = *(const float4*)(scale + col);
;             x0 = v[0] * c4.x; x1 = v[1] * c4.y; x2 = v[2] * c4.z; x3 = v[3] * c4.w;
;           } else {
;             x0 = v[0] * s; x1 = v[1] * s; x2 = v[2] * s; x3 = v[3] * s;
;           }
;           if (MODE == 1 && act) { x0 = gelu_f(x0); x1 = gelu_f(x1); x2 = gelu_f(x2); x3 = gelu_f(x3); }
;           o[n].x = pack2(x0, x1);
;           o[n].y = pack2(x2, x3);
;         }
;         auto rx = __builtin_amdgcn_permlane16_swap(o[0].x, o[1].x, false, false);
;         auto ry = __builtin_amdgcn_permlane16_swap(o[0].y, o[1].y, false, false);
;         const int colw = ecol + bj * HALF + wc * 32 + (fq & 1) * 16 + (fq >> 1) * 8;
;         *(uint4*)(C + (size_t)row * ldc + colw) = make_uint4(rx[0], ry[0], rx[1], ry[1]);
.LBB0_306:
	v_cvt_pk_bf16_f32 v54, v54, v55
	v_cvt_pk_bf16_f32 v55, v56, v57
	v_cvt_pk_bf16_f32 v56, v50, v51
	v_cvt_pk_bf16_f32 v57, v52, v53
	s_nop 0
	v_permlane16_swap_b32_e32 v54, v56
	v_permlane16_swap_b32_e32 v55, v57
	global_store_dwordx4 v[58:59], v[54:57], off offset:256
	s_and_b64 vcc, exec, s[4:5]
	v_mov_b32_e32 v50, v181
	v_pk_mul_f32 v[46:47], v[46:47], v[50:51] op_sel_hi:[1,0]
	v_pk_mul_f32 v[48:49], v[48:49], v[50:51] op_sel_hi:[1,0]
	s_cbranch_vccnz .LBB0_308
	v_pk_mul_f32 v[52:53], v[46:47], v[46:47]
	s_nop 0
	v_fmamk_f32 v0, v52, 0x3dd2d3e7, v209
	v_mul_f32_e64 v0, v0, -v46
	v_exp_f32_e32 v0, v0
	s_nop 0
	v_add_f32_e32 v0, 1.0, v0
	v_rcp_f32_e32 v52, v0
	v_fmamk_f32 v0, v53, 0x3dd2d3e7, v209
	v_mul_f32_e64 v0, v0, -v47
	v_exp_f32_e32 v0, v0
	s_nop 0
	v_add_f32_e32 v0, 1.0, v0
	v_rcp_f32_e32 v53, v0
	s_nop 0
	v_pk_mul_f32 v[46:47], v[46:47], v[52:53]
	v_pk_mul_f32 v[52:53], v[48:49], v[48:49]
	s_nop 0
	v_fmamk_f32 v0, v52, 0x3dd2d3e7, v209
	v_mul_f32_e64 v0, v0, -v48
	v_exp_f32_e32 v0, v0
	s_nop 0
	v_add_f32_e32 v0, 1.0, v0
	v_rcp_f32_e32 v52, v0
	v_fmamk_f32 v0, v53, 0x3dd2d3e7, v209
	v_mul_f32_e64 v0, v0, -v49
	v_exp_f32_e32 v0, v0
	s_nop 0
	v_add_f32_e32 v0, 1.0, v0
	v_rcp_f32_e32 v53, v0
	s_nop 0
	v_pk_mul_f32 v[48:49], v[48:49], v[52:53]

; template <int MODE>
; __device__ __forceinline__ void gemm_tile(const int ph, const int which, const int pm, const int pn) {
;     ...
;   for (int ai = 0; ai < 2; ++ai)
;     for (int m = 0; m < 4; ++m) {
;       const int row = browC + ai * HALF + wr * 64 + m * 16 + fr;
;       float s = 1.f;
;       if (MODE == 1) s = scale[row];
;       for (int bj = 0; bj < 2; ++bj) {
;         uint2 o[2];
; #pragma unroll
;         for (int n = 0; n < 2; ++n) {
;           const int col = ecol + bj * HALF + wc * 32 + n * 16 + fq * 4;
;           f32x4 v = acc[ai][bj][m][n];
;           float x0, x1, x2, x3;
;           if (MODE == 2) {
;             float4 c4 = *(const float4*)(scale + col);
;             x0 = v[0] * c4.x; x1 = v[1] * c4.y; x2 = v[2] * c4.z; x3 = v[3] * c4.w;
;           } else {
;             x0 = v[0] * s; x1 = v[1] * s; x2 = v[2] * s; x3 = v[3] * s;
;           }
;           if (MODE == 1 && act) { x0 = gelu_f(x0); x1 = gelu_f(x1); x2 = gelu_f(x2); x3 = gelu_f(x3); }
;           o[n].x = pack2(x0, x1);
;           o[n].y = pack2(x2, x3);
;         }
;         auto rx = __builtin_amdgcn_permlane16_swap(o[0].x, o[1].x, false, false);
;         auto ry = __builtin_amdgcn_permlane16_swap(o[0].y, o[1].y, false, false);
;         const int colw = ecol + bj * HALF + wc * 32 + (fq & 1) * 16 + (fq >> 1) * 8;
;         *(uint4*)(C + (size_t)row * ldc + colw) = make_uint4(rx[0], ry[0], rx[1], ry[1]);
.LBB0_314:
	v_cvt_pk_bf16_f32 v38, v38, v39
	v_cvt_pk_bf16_f32 v39, v40, v41
	v_cvt_pk_bf16_f32 v40, v34, v35
	v_cvt_pk_bf16_f32 v41, v36, v37
	s_nop 0
	v_permlane16_swap_b32_e32 v38, v40
	v_permlane16_swap_b32_e32 v39, v41
	global_store_dwordx4 v[42:43], v[38:41], off offset:256
	s_and_b64 vcc, exec, s[4:5]
	v_mov_b32_e32 v34, v182
	v_pk_mul_f32 v[30:31], v[30:31], v[34:35] op_sel_hi:[1,0]
	v_pk_mul_f32 v[32:33], v[32:33], v[34:35] op_sel_hi:[1,0]
	s_cbranch_vccnz .LBB0_316
	v_pk_mul_f32 v[36:37], v[30:31], v[30:31]
	s_nop 0
	v_fmamk_f32 v0, v36, 0x3dd2d3e7, v209
	v_mul_f32_e64 v0, v0, -v30
	v_exp_f32_e32 v0, v0
	s_nop 0
	v_add_f32_e32 v0, 1.0, v0
	v_rcp_f32_e32 v36, v0
	v_fmamk_f32 v0, v37, 0x3dd2d3e7, v209
	v_mul_f32_e64 v0, v0, -v31
	v_exp_f32_e32 v0, v0
	s_nop 0
	v_add_f32_e32 v0, 1.0, v0
	v_rcp_f32_e32 v37, v0
	s_nop 0
	v_pk_mul_f32 v[30:31], v[30:31], v[36:37]
	v_pk_mul_f32 v[36:37], v[32:33], v[32:33]
	s_nop 0
	v_fmamk_f32 v0, v36, 0x3dd2d3e7, v209
	v_mul_f32_e64 v0, v0, -v32
	v_exp_f32_e32 v0, v0
	s_nop 0
	v_add_f32_e32 v0, 1.0, v0
	v_rcp_f32_e32 v36, v0
	v_fmamk_f32 v0, v37, 0x3dd2d3e7, v209
	v_mul_f32_e64 v0, v0, -v33
	v_exp_f32_e32 v0, v0
	s_nop 0
	v_add_f32_e32 v0, 1.0, v0
	v_rcp_f32_e32 v37, v0
	s_nop 0
	v_pk_mul_f32 v[32:33], v[32:33], v[36:37]

; template <int MODE>
; __device__ __forceinline__ void gemm_tile(const int ph, const int which, const int pm, const int pn) {
;     ...
;   for (int ai = 0; ai < 2; ++ai)
;     for (int m = 0; m < 4; ++m) {
;       const int row = browC + ai * HALF + wr * 64 + m * 16 + fr;
;       float s = 1.f;
;       if (MODE == 1) s = scale[row];
;       for (int bj = 0; bj < 2; ++bj) {
;         uint2 o[2];
; #pragma unroll
;         for (int n = 0; n < 2; ++n) {
;           const int col = ecol + bj * HALF + wc * 32 + n * 16 + fq * 4;
;           f32x4 v = acc[ai][bj][m][n];
;           float x0, x1, x2, x3;
;           if (MODE == 2) {
;             float4 c4 = *(const float4*)(scale + col);
;             x0 = v[0] * c4.x; x1 = v[1] * c4.y; x2 = v[2] * c4.z; x3 = v[3] * c4.w;
;           } else {
;             x0 = v[0] * s; x1 = v[1] * s; x2 = v[2] * s; x3 = v[3] * s;
;           }
;           if (MODE == 1 && act) { x0 = gelu_f(x0); x1 = gelu_f(x1); x2 = gelu_f(x2); x3 = gelu_f(x3); }
;           o[n].x = pack2(x0, x1);
;           o[n].y = pack2(x2, x3);
;         }
;         auto rx = __builtin_amdgcn_permlane16_swap(o[0].x, o[1].x, false, false);
;         auto ry = __builtin_amdgcn_permlane16_swap(o[0].y, o[1].y, false, false);
;         const int colw = ecol + bj * HALF + wc * 32 + (fq & 1) * 16 + (fq >> 1) * 8;
;         *(uint4*)(C + (size_t)row * ldc + colw) = make_uint4(rx[0], ry[0], rx[1], ry[1]);
.LBB0_322:
	v_cvt_pk_bf16_f32 v22, v22, v23
	v_cvt_pk_bf16_f32 v23, v24, v25
	v_cvt_pk_bf16_f32 v24, v18, v19
	v_cvt_pk_bf16_f32 v25, v20, v21
	s_nop 0
	v_permlane16_swap_b32_e32 v22, v24
	v_permlane16_swap_b32_e32 v23, v25
	global_store_dwordx4 v[26:27], v[22:25], off offset:256
	s_and_b64 vcc, exec, s[4:5]
	v_mov_b32_e32 v18, v183
	v_pk_mul_f32 v[14:15], v[14:15], v[18:19] op_sel_hi:[1,0]
	v_pk_mul_f32 v[16:17], v[16:17], v[18:19] op_sel_hi:[1,0]
	s_cbranch_vccnz .LBB0_324
	v_pk_mul_f32 v[20:21], v[14:15], v[14:15]
	s_nop 0
	v_fmamk_f32 v0, v20, 0x3dd2d3e7, v209
	v_mul_f32_e64 v0, v0, -v14
	v_exp_f32_e32 v0, v0
	s_nop 0
	v_add_f32_e32 v0, 1.0, v0
	v_rcp_f32_e32 v20, v0
	v_fmamk_f32 v0, v21, 0x3dd2d3e7, v209
	v_mul_f32_e64 v0, v0, -v15
	v_exp_f32_e32 v0, v0
	s_nop 0
	v_add_f32_e32 v0, 1.0, v0
	v_rcp_f32_e32 v21, v0
	s_nop 0
	v_pk_mul_f32 v[14:15], v[14:15], v[20:21]
	v_pk_mul_f32 v[20:21], v[16:17], v[16:17]
	s_nop 0
	v_fmamk_f32 v0, v20, 0x3dd2d3e7, v209
	v_mul_f32_e64 v0, v0, -v16
	v_exp_f32_e32 v0, v0
	s_nop 0
	v_add_f32_e32 v0, 1.0, v0
	v_rcp_f32_e32 v20, v0
	v_fmamk_f32 v0, v21, 0x3dd2d3e7, v209
	v_mul_f32_e64 v0, v0, -v17
	v_exp_f32_e32 v0, v0
	s_nop 0
	v_add_f32_e32 v0, 1.0, v0
	v_rcp_f32_e32 v21, v0
	s_nop 0
	v_pk_mul_f32 v[16:17], v[16:17], v[20:21]
